# P0 rmsnorm loop: wave sums via DPP (quad_perm / row_mirror / row_bcast + readlane) and xor-1 store shuffles via DPP instead of 40 ds_bpermute round trips per iteration
# speedup vs baseline: 1.0040x; 1.0040x over previous
.LBB0_62:
	s_or_saveexec_b64 s[8:9], s[8:9]
	v_ashrrev_i32_e32 v89, 31, v88
	s_xor_b64 exec, exec, s[8:9]
	v_mov_b64_e32 v[18:19], v[88:89]
	s_or_b64 exec, exec, s[8:9]
	v_lshlrev_b64 v[18:19], 12, v[18:19]
	v_lshl_add_u64 v[18:19], v[20:21], 0, v[18:19]
	v_lshl_add_u64 v[18:19], v[18:19], 0, v[82:83]
	global_load_dwordx4 v[78:81], v[18:19], off
	global_load_dwordx4 v[74:77], v[18:19], off offset:1024
	global_load_dwordx4 v[66:69], v[18:19], off offset:3072
	global_load_dwordx4 v[70:73], v[18:19], off offset:2048
	v_add_co_u32_e32 v20, vcc, 0x1000, v18
	s_nop 1
	v_addc_co_u32_e32 v21, vcc, 0, v19, vcc
	v_add_co_u32_e32 v22, vcc, 0x2000, v18
	global_load_dwordx4 v[62:65], v[20:21], off
	global_load_dwordx4 v[58:61], v[20:21], off offset:1024
	global_load_dwordx4 v[54:57], v[20:21], off offset:2048
	global_load_dwordx4 v[50:53], v[20:21], off offset:3072
	v_addc_co_u32_e32 v23, vcc, 0, v19, vcc
	v_add_co_u32_e32 v18, vcc, 0x3000, v18
	global_load_dwordx4 v[46:49], v[22:23], off
	global_load_dwordx4 v[42:45], v[22:23], off offset:1024
	global_load_dwordx4 v[38:41], v[22:23], off offset:2048
	global_load_dwordx4 v[34:37], v[22:23], off offset:3072
	v_addc_co_u32_e32 v19, vcc, 0, v19, vcc
	global_load_dwordx4 v[30:33], v[18:19], off
	global_load_dwordx4 v[26:29], v[18:19], off offset:1024
	global_load_dwordx4 v[22:25], v[18:19], off offset:2048
	s_nop 0
	global_load_dwordx4 v[18:21], v[18:19], off offset:3072
	s_waitcnt vmcnt(15)
	v_pk_mul_f32 v[102:103], v[80:81], v[80:81]
	v_cmp_lt_i32_e32 vcc, v96, v95
	v_pk_mul_f32 v[104:105], v[78:79], v[78:79]
	s_waitcnt vmcnt(14)
	v_pk_mul_f32 v[106:107], v[76:77], v[76:77]
	v_pk_mul_f32 v[108:109], v[74:75], v[74:75]
	v_cndmask_b32_e32 v90, v94, v96, vcc
	v_pk_mov_b32 v[112:113], v[104:105], v[102:103] op_sel:[1,0]
	v_mov_b32_e32 v105, v103
	v_pk_mov_b32 v[102:103], v[108:109], v[106:107] op_sel:[1,0]
	v_mov_b32_e32 v109, v107
	v_lshlrev_b32_e32 v101, 2, v90
	s_waitcnt vmcnt(12)
	v_mul_f32_e32 v90, v71, v71
	v_mul_f32_e32 v110, v73, v73
	v_pk_add_f32 v[104:105], v[112:113], v[104:105]
	v_pk_add_f32 v[102:103], v[102:103], v[108:109]
	v_mul_f32_e32 v114, v66, v66
	v_mul_f32_e32 v115, v67, v67
	v_mul_f32_e32 v116, v68, v68
	v_mul_f32_e32 v117, v69, v69
	v_pk_fma_f32 v[106:107], v[70:71], v[70:71], v[90:91] op_sel_hi:[1,1,0]
	v_pk_fma_f32 v[110:111], v[72:73], v[72:73], v[110:111] op_sel_hi:[1,1,0]
	v_pk_add_f32 v[104:105], v[104:105], v[104:105] op_sel:[0,1] op_sel_hi:[1,0]
	v_pk_add_f32 v[102:103], v[102:103], v[102:103] op_sel:[0,1] op_sel_hi:[1,0]
	v_mov_b32_e32 v107, v116
	v_mov_b32_e32 v111, v117
	v_mov_b32_e32 v105, v114
	v_mov_b32_e32 v103, v115
	v_pk_add_f32 v[102:103], v[104:105], v[102:103]
	v_pk_add_f32 v[104:105], v[106:107], v[110:111]
	v_cmp_lt_i32_e32 vcc, v97, v95
	v_pk_add_f32 v[102:103], v[102:103], v[104:105]
	s_nop 0
	v_add_f32_e32 v102, v102, v103
	s_nop 1
	v_add_f32_dpp v102, v102, v102 quad_perm:[1,0,3,2] row_mask:0xf bank_mask:0xf
	s_nop 1
	v_add_f32_dpp v102, v102, v102 quad_perm:[2,3,0,1] row_mask:0xf bank_mask:0xf
	s_nop 1
	v_add_f32_dpp v102, v102, v102 row_half_mirror row_mask:0xf bank_mask:0xf
	s_nop 1
	v_add_f32_dpp v102, v102, v102 row_mirror row_mask:0xf bank_mask:0xf
	s_nop 1
	v_add_f32_dpp v102, v102, v102 row_bcast:15 row_mask:0xa bank_mask:0xf
	s_nop 1
	v_add_f32_dpp v102, v102, v102 row_bcast:31 row_mask:0xc bank_mask:0xf
	s_nop 0
	v_readlane_b32 s98, v102, 63
	s_nop 1
	v_mov_b32_e32 v102, s98
	v_fmamk_f32 v102, v102, 0x3a800000, v92
	s_and_saveexec_b64 s[10:11], s[0:1]
	s_cbranch_execz .LBB0_66
	v_mul_f32_e32 v107, 0x4f800000, v102
	v_cmp_gt_f32_e32 vcc, s25, v102
	s_nop 1
	v_cndmask_b32_e32 v107, v102, v107, vcc
	v_sqrt_f32_e32 v108, v107
	s_nop 0
	v_add_u32_e32 v109, -1, v108
	v_fma_f32 v111, -v109, v108, v107
	v_add_u32_e32 v110, 1, v108
	v_cmp_ge_f32_e64 s[8:9], 0, v111
	s_nop 1
	v_cndmask_b32_e64 v109, v108, v109, s[8:9]
	v_fma_f32 v108, -v110, v108, v107
	v_cmp_lt_f32_e64 s[8:9], 0, v108
	s_nop 1
	v_cndmask_b32_e64 v108, v109, v110, s[8:9]
	v_mul_f32_e32 v109, 0x37800000, v108
	v_cndmask_b32_e32 v108, v108, v109, vcc
	v_cmp_class_f32_e32 vcc, v107, v93
	s_nop 1
	v_cndmask_b32_e32 v107, v108, v107, vcc
	v_lshl_add_u64 v[108:109], v[88:89], 2, s[16:17]
	global_store_dword v[108:109], v107, off
.LBB0_66:
	s_or_b64 exec, exec, s[10:11]
	s_waitcnt vmcnt(11)
	v_pk_mul_f32 v[108:109], v[64:65], v[64:65]
	v_pk_mul_f32 v[110:111], v[62:63], v[62:63]
	s_waitcnt vmcnt(8)
	v_mul_f32_e32 v107, v50, v50
	v_pk_mov_b32 v[112:113], v[110:111], v[108:109] op_sel:[1,0]
	v_mov_b32_e32 v111, v109
	v_pk_add_f32 v[108:109], v[112:113], v[110:111]
	v_pk_mul_f32 v[110:111], v[60:61], v[60:61]
	v_pk_mul_f32 v[112:113], v[58:59], v[58:59]
	v_pk_add_f32 v[108:109], v[108:109], v[108:109] op_sel:[0,1] op_sel_hi:[1,0]
	v_pk_mov_b32 v[114:115], v[112:113], v[110:111] op_sel:[1,0]
	v_mov_b32_e32 v113, v111
	v_pk_add_f32 v[110:111], v[114:115], v[112:113]
	v_mul_f32_e32 v112, v51, v51
	v_pk_add_f32 v[110:111], v[110:111], v[110:111] op_sel:[0,1] op_sel_hi:[1,0]
	v_mov_b32_e32 v109, v107
	v_mov_b32_e32 v111, v112
	v_pk_add_f32 v[108:109], v[108:109], v[110:111]
	v_mul_f32_e32 v110, v55, v55
	v_mul_f32_e32 v113, v52, v52
	v_pk_fma_f32 v[110:111], v[54:55], v[54:55], v[110:111] op_sel_hi:[1,1,0]
	v_mul_f32_e32 v112, v57, v57
	v_mul_f32_e32 v114, v53, v53
	v_mov_b32_e32 v111, v113
	v_pk_fma_f32 v[112:113], v[56:57], v[56:57], v[112:113] op_sel_hi:[1,1,0]
	s_nop 0
	v_mov_b32_e32 v113, v114
	v_pk_add_f32 v[110:111], v[110:111], v[112:113]
	s_nop 0
	v_pk_add_f32 v[108:109], v[108:109], v[110:111]
	s_nop 0
	v_add_f32_e32 v107, v108, v109
	s_nop 1
	v_add_f32_dpp v107, v107, v107 quad_perm:[1,0,3,2] row_mask:0xf bank_mask:0xf
	s_nop 1
	v_add_f32_dpp v107, v107, v107 quad_perm:[2,3,0,1] row_mask:0xf bank_mask:0xf
	s_nop 1
	v_add_f32_dpp v107, v107, v107 row_half_mirror row_mask:0xf bank_mask:0xf
	s_nop 1
	v_add_f32_dpp v107, v107, v107 row_mirror row_mask:0xf bank_mask:0xf
	s_nop 1
	v_add_f32_dpp v107, v107, v107 row_bcast:15 row_mask:0xa bank_mask:0xf
	s_nop 1
	v_add_f32_dpp v107, v107, v107 row_bcast:31 row_mask:0xc bank_mask:0xf
	s_nop 0
	v_readlane_b32 s98, v107, 63
	s_nop 1
	v_mov_b32_e32 v107, s98
	v_fmamk_f32 v107, v107, 0x3a800000, v92
	s_and_saveexec_b64 s[10:11], s[0:1]
	s_cbranch_execz .LBB0_68
	v_mul_f32_e32 v108, 0x4f800000, v107
	v_cmp_gt_f32_e32 vcc, s25, v107
	s_nop 1
	v_cndmask_b32_e32 v108, v107, v108, vcc
	v_sqrt_f32_e32 v109, v108
	s_nop 0
	v_add_u32_e32 v110, -1, v109
	v_fma_f32 v112, -v110, v109, v108
	v_add_u32_e32 v111, 1, v109
	v_cmp_ge_f32_e64 s[8:9], 0, v112
	s_nop 1
	v_cndmask_b32_e64 v110, v109, v110, s[8:9]
	v_fma_f32 v109, -v111, v109, v108
	v_cmp_lt_f32_e64 s[8:9], 0, v109
	s_nop 1
	v_cndmask_b32_e64 v109, v110, v111, s[8:9]
	v_mul_f32_e32 v110, 0x37800000, v109
	v_cndmask_b32_e32 v109, v109, v110, vcc
	v_cmp_class_f32_e32 vcc, v108, v93
	s_nop 1
	v_cndmask_b32_e32 v110, v109, v108, vcc
	v_lshl_add_u64 v[108:109], v[88:89], 2, s[16:17]
	global_store_dword v[108:109], v110, off offset:4
.LBB0_68:
	s_or_b64 exec, exec, s[10:11]
	s_waitcnt vmcnt(7)
	v_pk_mul_f32 v[108:109], v[48:49], v[48:49]
	v_pk_mul_f32 v[110:111], v[46:47], v[46:47]
	s_nop 0
	v_pk_mov_b32 v[112:113], v[110:111], v[108:109] op_sel:[1,0]
	v_mov_b32_e32 v111, v109
	v_pk_add_f32 v[108:109], v[112:113], v[110:111]
	s_waitcnt vmcnt(6)
	v_pk_mul_f32 v[110:111], v[44:45], v[44:45]
	v_pk_mul_f32 v[112:113], v[42:43], v[42:43]
	v_pk_add_f32 v[108:109], v[108:109], v[108:109] op_sel:[0,1] op_sel_hi:[1,0]
	v_pk_mov_b32 v[114:115], v[112:113], v[110:111] op_sel:[1,0]
	v_mov_b32_e32 v113, v111
	v_pk_add_f32 v[110:111], v[114:115], v[112:113]
	s_waitcnt vmcnt(4)
	v_mul_f32_e32 v112, v34, v34
	v_mul_f32_e32 v113, v35, v35
	v_pk_add_f32 v[110:111], v[110:111], v[110:111] op_sel:[0,1] op_sel_hi:[1,0]
	v_mov_b32_e32 v109, v112
	v_mov_b32_e32 v111, v113
	v_pk_add_f32 v[108:109], v[108:109], v[110:111]
	v_mul_f32_e32 v110, v39, v39
	v_mul_f32_e32 v112, v41, v41
	v_mul_f32_e32 v114, v36, v36
	v_mul_f32_e32 v115, v37, v37
	v_pk_fma_f32 v[110:111], v[38:39], v[38:39], v[110:111] op_sel_hi:[1,1,0]
	v_pk_fma_f32 v[112:113], v[40:41], v[40:41], v[112:113] op_sel_hi:[1,1,0]
	v_mov_b32_e32 v111, v114
	v_mov_b32_e32 v113, v115
	v_pk_add_f32 v[110:111], v[110:111], v[112:113]
	s_nop 0
	v_pk_add_f32 v[108:109], v[108:109], v[110:111]
	s_nop 0
	v_add_f32_e32 v108, v108, v109
	s_nop 1
	v_add_f32_dpp v108, v108, v108 quad_perm:[1,0,3,2] row_mask:0xf bank_mask:0xf
	s_nop 1
	v_add_f32_dpp v108, v108, v108 quad_perm:[2,3,0,1] row_mask:0xf bank_mask:0xf
	s_nop 1
	v_add_f32_dpp v108, v108, v108 row_half_mirror row_mask:0xf bank_mask:0xf
	s_nop 1
	v_add_f32_dpp v108, v108, v108 row_mirror row_mask:0xf bank_mask:0xf
	s_nop 1
	v_add_f32_dpp v108, v108, v108 row_bcast:15 row_mask:0xa bank_mask:0xf
	s_nop 1
	v_add_f32_dpp v108, v108, v108 row_bcast:31 row_mask:0xc bank_mask:0xf
	s_nop 0
	v_readlane_b32 s98, v108, 63
	s_nop 1
	v_mov_b32_e32 v108, s98
	v_fmamk_f32 v108, v108, 0x3a800000, v92
	s_and_saveexec_b64 s[10:11], s[0:1]
	s_cbranch_execz .LBB0_70
	v_mul_f32_e32 v109, 0x4f800000, v108
	v_cmp_gt_f32_e32 vcc, s25, v108
	s_nop 1
	v_cndmask_b32_e32 v109, v108, v109, vcc
	v_sqrt_f32_e32 v110, v109
	s_nop 0
	v_add_u32_e32 v111, -1, v110
	v_fma_f32 v113, -v111, v110, v109
	v_add_u32_e32 v112, 1, v110
	v_cmp_ge_f32_e64 s[8:9], 0, v113
	s_nop 1
	v_cndmask_b32_e64 v111, v110, v111, s[8:9]
	v_fma_f32 v110, -v112, v110, v109
	v_cmp_lt_f32_e64 s[8:9], 0, v110
	s_nop 1
	v_cndmask_b32_e64 v110, v111, v112, s[8:9]
	v_mul_f32_e32 v111, 0x37800000, v110
	v_cndmask_b32_e32 v110, v110, v111, vcc
	v_cmp_class_f32_e32 vcc, v109, v93
	s_nop 1
	v_cndmask_b32_e32 v109, v110, v109, vcc
	v_lshl_add_u64 v[110:111], v[88:89], 2, s[16:17]
	global_store_dword v[110:111], v109, off offset:8
.LBB0_70:
	s_or_b64 exec, exec, s[10:11]
	s_waitcnt vmcnt(3)
	v_pk_mul_f32 v[110:111], v[32:33], v[32:33]
	v_pk_mul_f32 v[112:113], v[30:31], v[30:31]
	s_waitcnt vmcnt(0)
	v_mul_f32_e32 v109, v18, v18
	v_pk_mov_b32 v[114:115], v[112:113], v[110:111] op_sel:[1,0]
	v_mov_b32_e32 v113, v111
	v_pk_add_f32 v[110:111], v[114:115], v[112:113]
	v_pk_mul_f32 v[112:113], v[28:29], v[28:29]
	v_pk_mul_f32 v[114:115], v[26:27], v[26:27]
	v_pk_add_f32 v[110:111], v[110:111], v[110:111] op_sel:[0,1] op_sel_hi:[1,0]
	v_pk_mov_b32 v[116:117], v[114:115], v[112:113] op_sel:[1,0]
	v_mov_b32_e32 v115, v113
	v_pk_add_f32 v[112:113], v[116:117], v[114:115]
	v_mul_f32_e32 v114, v19, v19
	v_pk_add_f32 v[112:113], v[112:113], v[112:113] op_sel:[0,1] op_sel_hi:[1,0]
	v_mov_b32_e32 v111, v109
	v_mov_b32_e32 v113, v114
	v_pk_add_f32 v[110:111], v[110:111], v[112:113]
	v_mul_f32_e32 v112, v23, v23
	v_mul_f32_e32 v115, v20, v20
	v_pk_fma_f32 v[112:113], v[22:23], v[22:23], v[112:113] op_sel_hi:[1,1,0]
	v_mul_f32_e32 v114, v25, v25
	v_mul_f32_e32 v116, v21, v21
	v_mov_b32_e32 v113, v115
	v_pk_fma_f32 v[114:115], v[24:25], v[24:25], v[114:115] op_sel_hi:[1,1,0]
	s_nop 0
	v_mov_b32_e32 v115, v116
	v_pk_add_f32 v[112:113], v[112:113], v[114:115]
	s_nop 0
	v_pk_add_f32 v[110:111], v[110:111], v[112:113]
	s_nop 0
	v_add_f32_e32 v109, v110, v111
	s_nop 1
	v_add_f32_dpp v109, v109, v109 quad_perm:[1,0,3,2] row_mask:0xf bank_mask:0xf
	s_nop 1
	v_add_f32_dpp v109, v109, v109 quad_perm:[2,3,0,1] row_mask:0xf bank_mask:0xf
	s_nop 1
	v_add_f32_dpp v109, v109, v109 row_half_mirror row_mask:0xf bank_mask:0xf
	s_nop 1
	v_add_f32_dpp v109, v109, v109 row_mirror row_mask:0xf bank_mask:0xf
	s_nop 1
	v_add_f32_dpp v109, v109, v109 row_bcast:15 row_mask:0xa bank_mask:0xf
	s_nop 1
	v_add_f32_dpp v109, v109, v109 row_bcast:31 row_mask:0xc bank_mask:0xf
	s_nop 0
	v_readlane_b32 s98, v109, 63
	s_nop 1
	s_and_saveexec_b64 s[8:9], s[6:7]
	s_xor_b64 s[8:9], exec, s[8:9]
	s_or_saveexec_b64 s[10:11], s[8:9]
	v_mov_b32_e32 v90, s98
	v_fmamk_f32 v90, v90, 0x3a800000, v92
	s_xor_b64 exec, exec, s[10:11]
	s_cbranch_execz .LBB0_72
	v_mul_f32_e32 v103, 0x4f800000, v90
	v_cmp_gt_f32_e32 vcc, s25, v90
	s_nop 1
	v_cndmask_b32_e32 v103, v90, v103, vcc
	v_sqrt_f32_e32 v104, v103
	s_nop 0
	v_add_u32_e32 v105, -1, v104
	v_fma_f32 v109, -v105, v104, v103
	v_add_u32_e32 v106, 1, v104
	v_cmp_ge_f32_e64 s[8:9], 0, v109
	s_nop 1
	v_cndmask_b32_e64 v105, v104, v105, s[8:9]
	v_fma_f32 v104, -v106, v104, v103
	v_cmp_lt_f32_e64 s[8:9], 0, v104
	s_nop 1
	v_cndmask_b32_e64 v104, v105, v106, s[8:9]
	v_mul_f32_e32 v105, 0x37800000, v104
	v_cndmask_b32_e32 v104, v104, v105, vcc
	v_cmp_class_f32_e32 vcc, v103, v93
	s_nop 1
	v_cndmask_b32_e32 v103, v104, v103, vcc
	v_lshl_add_u64 v[104:105], v[88:89], 2, s[16:17]
	global_store_dword v[104:105], v103, off offset:12
.LBB0_72:
	s_or_b64 exec, exec, s[10:11]
	v_mul_f32_e32 v103, 0x4b800000, v90
	v_cmp_gt_f32_e32 vcc, s26, v90
	v_cmp_gt_f32_e64 s[8:9], s26, v108
	v_mul_f32_e32 v105, 0x4b800000, v107
	v_cndmask_b32_e32 v90, v90, v103, vcc
	v_rsq_f32_e32 v90, v90
	v_mul_f32_e32 v103, 0x4b800000, v108
	v_cndmask_b32_e64 v103, v108, v103, s[8:9]
	v_rsq_f32_e32 v103, v103
	v_mul_f32_e32 v104, 0x45800000, v90
	v_cndmask_b32_e32 v90, v90, v104, vcc
	v_cmp_gt_f32_e32 vcc, s26, v107
	v_mul_f32_e32 v106, 0x4b800000, v102
	v_cmp_gt_f32_e64 s[10:11], s26, v102
	v_cndmask_b32_e32 v105, v107, v105, vcc
	v_rsq_f32_e32 v105, v105
	v_cndmask_b32_e64 v102, v102, v106, s[10:11]
	v_rsq_f32_e32 v106, v102
	v_mul_f32_e32 v104, 0x45800000, v103
	v_cndmask_b32_e64 v102, v103, v104, s[8:9]
	v_mul_f32_e32 v103, 0x45800000, v105
	v_cndmask_b32_e32 v104, v105, v103, vcc
	v_mul_f32_e32 v103, 0x45800000, v106
	v_cndmask_b32_e64 v106, v106, v103, s[10:11]
	v_pk_mul_f32 v[78:79], v[78:79], v[106:107] op_sel_hi:[1,0]
	v_pk_mul_f32 v[74:75], v[74:75], v[106:107] op_sel_hi:[1,0]
	v_pk_mul_f32 v[76:77], v[76:77], v[106:107] op_sel_hi:[1,0]
	v_pk_mul_f32 v[72:73], v[72:73], v[106:107] op_sel_hi:[1,0]
	v_pk_mul_f32 v[66:67], v[66:67], v[106:107] op_sel_hi:[1,0]
	v_pk_mul_f32 v[80:81], v[80:81], v[106:107] op_sel_hi:[1,0]
	v_pk_mul_f32 v[78:79], v[2:3], v[78:79]
	v_pk_mul_f32 v[76:77], v[8:9], v[76:77]
	v_pk_mul_f32 v[74:75], v[6:7], v[74:75]
	v_pk_mul_f32 v[70:71], v[70:71], v[106:107] op_sel_hi:[1,0]
	v_pk_mul_f32 v[72:73], v[12:13], v[72:73]
	v_pk_mul_f32 v[66:67], v[14:15], v[66:67]
	v_pk_mul_f32 v[80:81], v[4:5], v[80:81]
	v_cvt_pk_bf16_f32 v78, v78, v79
	v_pk_mul_f32 v[70:71], v[10:11], v[70:71]
	v_cvt_pk_bf16_f32 v79, v80, v81
	v_cvt_pk_bf16_f32 v74, v74, v75
	v_cvt_pk_bf16_f32 v75, v76, v77
	v_pk_mul_f32 v[68:69], v[68:69], v[106:107] op_sel_hi:[1,0]
	v_cvt_pk_bf16_f32 v76, v70, v71
	v_cvt_pk_bf16_f32 v72, v72, v73
	v_cvt_pk_bf16_f32 v73, v66, v67
	v_cndmask_b32_e64 v66, v78, v74, s[4:5]
	v_cndmask_b32_e64 v67, v79, v75, s[4:5]
	s_nop 1
	v_mov_b32_dpp v66, v66 quad_perm:[1,0,3,2] row_mask:0xf bank_mask:0xf
	s_nop 1
	v_mov_b32_dpp v67, v67 quad_perm:[1,0,3,2] row_mask:0xf bank_mask:0xf
	v_pk_mul_f32 v[68:69], v[16:17], v[68:69]
	v_lshlrev_b64 v[70:71], 11, v[88:89]
	v_cvt_pk_bf16_f32 v77, v68, v69
	s_waitcnt lgkmcnt(1)
	v_cndmask_b32_e64 v68, v74, v66, s[4:5]
	s_waitcnt lgkmcnt(0)
	v_cndmask_b32_e64 v69, v75, v67, s[4:5]
	v_cndmask_b32_e64 v74, v76, v73, s[4:5]
	v_cndmask_b32_e64 v75, v72, v77, s[4:5]
	s_nop 1
	v_mov_b32_dpp v74, v74 quad_perm:[1,0,3,2] row_mask:0xf bank_mask:0xf
	s_nop 1
	v_mov_b32_dpp v75, v75 quad_perm:[1,0,3,2] row_mask:0xf bank_mask:0xf
	v_cndmask_b32_e64 v66, v66, v78, s[4:5]
	v_cndmask_b32_e64 v67, v67, v79, s[4:5]
	v_lshl_add_u64 v[70:71], v[86:87], 0, v[70:71]
	v_pk_mul_f32 v[62:63], v[62:63], v[104:105] op_sel_hi:[1,0]
	v_pk_mul_f32 v[58:59], v[58:59], v[104:105] op_sel_hi:[1,0]
	v_pk_mul_f32 v[60:61], v[60:61], v[104:105] op_sel_hi:[1,0]
	v_pk_mul_f32 v[56:57], v[56:57], v[104:105] op_sel_hi:[1,0]
	v_pk_mul_f32 v[50:51], v[50:51], v[104:105] op_sel_hi:[1,0]
	global_store_dwordx4 v[70:71], v[66:69], off
	v_pk_mul_f32 v[64:65], v[64:65], v[104:105] op_sel_hi:[1,0]
	v_pk_mul_f32 v[62:63], v[2:3], v[62:63]
	s_waitcnt lgkmcnt(1)
	v_cndmask_b32_e64 v68, v73, v74, s[4:5]
	v_cndmask_b32_e64 v66, v74, v76, s[4:5]
	s_waitcnt lgkmcnt(0)
	v_cndmask_b32_e64 v69, v77, v75, s[4:5]
	v_cndmask_b32_e64 v67, v75, v72, s[4:5]
	v_pk_mul_f32 v[60:61], v[8:9], v[60:61]
	v_pk_mul_f32 v[58:59], v[6:7], v[58:59]
	v_pk_mul_f32 v[54:55], v[54:55], v[104:105] op_sel_hi:[1,0]
	v_pk_mul_f32 v[56:57], v[12:13], v[56:57]
	v_pk_mul_f32 v[52:53], v[52:53], v[104:105] op_sel_hi:[1,0]
	v_pk_mul_f32 v[50:51], v[14:15], v[50:51]
	global_store_dwordx4 v[70:71], v[66:69], off offset:1024
	v_pk_mul_f32 v[64:65], v[4:5], v[64:65]
	v_cvt_pk_bf16_f32 v62, v62, v63
	v_pk_mul_f32 v[54:55], v[10:11], v[54:55]
	v_cvt_pk_bf16_f32 v63, v64, v65
	v_cvt_pk_bf16_f32 v58, v58, v59
	v_cvt_pk_bf16_f32 v59, v60, v61
	v_pk_mul_f32 v[52:53], v[16:17], v[52:53]
	v_cvt_pk_bf16_f32 v60, v54, v55
	v_cvt_pk_bf16_f32 v56, v56, v57
	v_cvt_pk_bf16_f32 v57, v50, v51
	v_cndmask_b32_e64 v51, v62, v58, s[4:5]
	v_cvt_pk_bf16_f32 v61, v52, v53
	s_nop 1
	v_mov_b32_dpp v53, v51 quad_perm:[1,0,3,2] row_mask:0xf bank_mask:0xf
	v_cndmask_b32_e64 v51, v63, v59, s[4:5]
	s_nop 1
	v_mov_b32_dpp v64, v51 quad_perm:[1,0,3,2] row_mask:0xf bank_mask:0xf
	v_add_u32_e32 v50, 1, v88
	v_ashrrev_i32_e32 v51, 31, v50
	v_lshlrev_b64 v[54:55], 11, v[50:51]
	s_waitcnt lgkmcnt(1)
	v_cndmask_b32_e64 v52, v58, v53, s[4:5]
	v_cndmask_b32_e64 v50, v53, v62, s[4:5]
	s_waitcnt lgkmcnt(0)
	v_cndmask_b32_e64 v53, v59, v64, s[4:5]
	v_cndmask_b32_e64 v58, v60, v57, s[4:5]
	v_cndmask_b32_e64 v59, v56, v61, s[4:5]
	s_nop 1
	v_mov_b32_dpp v58, v58 quad_perm:[1,0,3,2] row_mask:0xf bank_mask:0xf
	s_nop 1
	v_mov_b32_dpp v59, v59 quad_perm:[1,0,3,2] row_mask:0xf bank_mask:0xf
	v_cndmask_b32_e64 v51, v64, v63, s[4:5]
	v_lshl_add_u64 v[54:55], v[86:87], 0, v[54:55]
	v_pk_mul_f32 v[46:47], v[46:47], v[102:103] op_sel_hi:[1,0]
	v_pk_mul_f32 v[42:43], v[42:43], v[102:103] op_sel_hi:[1,0]
	v_pk_mul_f32 v[44:45], v[44:45], v[102:103] op_sel_hi:[1,0]
	v_pk_mul_f32 v[40:41], v[40:41], v[102:103] op_sel_hi:[1,0]
	v_pk_mul_f32 v[34:35], v[34:35], v[102:103] op_sel_hi:[1,0]
	global_store_dwordx4 v[54:55], v[50:53], off
	v_pk_mul_f32 v[48:49], v[48:49], v[102:103] op_sel_hi:[1,0]
	v_pk_mul_f32 v[46:47], v[2:3], v[46:47]
	s_waitcnt lgkmcnt(1)
	v_cndmask_b32_e64 v52, v57, v58, s[4:5]
	v_cndmask_b32_e64 v50, v58, v60, s[4:5]
	s_waitcnt lgkmcnt(0)
	v_cndmask_b32_e64 v53, v61, v59, s[4:5]
	v_cndmask_b32_e64 v51, v59, v56, s[4:5]
	v_pk_mul_f32 v[44:45], v[8:9], v[44:45]
	v_pk_mul_f32 v[42:43], v[6:7], v[42:43]
	v_pk_mul_f32 v[38:39], v[38:39], v[102:103] op_sel_hi:[1,0]
	v_pk_mul_f32 v[40:41], v[12:13], v[40:41]
	v_pk_mul_f32 v[36:37], v[36:37], v[102:103] op_sel_hi:[1,0]
	v_pk_mul_f32 v[34:35], v[14:15], v[34:35]
	global_store_dwordx4 v[54:55], v[50:53], off offset:1024
	v_pk_mul_f32 v[48:49], v[4:5], v[48:49]
	v_cvt_pk_bf16_f32 v46, v46, v47
	v_pk_mul_f32 v[38:39], v[10:11], v[38:39]
	v_cvt_pk_bf16_f32 v47, v48, v49
	v_cvt_pk_bf16_f32 v42, v42, v43
	v_cvt_pk_bf16_f32 v43, v44, v45
	v_pk_mul_f32 v[36:37], v[16:17], v[36:37]
	v_cvt_pk_bf16_f32 v44, v38, v39
	v_cvt_pk_bf16_f32 v40, v40, v41
	v_cvt_pk_bf16_f32 v41, v34, v35
	v_cndmask_b32_e64 v35, v46, v42, s[4:5]
	v_cvt_pk_bf16_f32 v45, v36, v37
	s_nop 1
	v_mov_b32_dpp v37, v35 quad_perm:[1,0,3,2] row_mask:0xf bank_mask:0xf
	v_cndmask_b32_e64 v35, v47, v43, s[4:5]
	s_nop 1
	v_mov_b32_dpp v48, v35 quad_perm:[1,0,3,2] row_mask:0xf bank_mask:0xf
	v_add_u32_e32 v34, 2, v88
	v_ashrrev_i32_e32 v35, 31, v34
	v_lshlrev_b64 v[38:39], 11, v[34:35]
	s_waitcnt lgkmcnt(1)
	v_cndmask_b32_e64 v36, v42, v37, s[4:5]
	v_cndmask_b32_e64 v34, v37, v46, s[4:5]
	s_waitcnt lgkmcnt(0)
	v_cndmask_b32_e64 v37, v43, v48, s[4:5]
	v_cndmask_b32_e64 v42, v44, v41, s[4:5]
	v_cndmask_b32_e64 v43, v40, v45, s[4:5]
	s_nop 1
	v_mov_b32_dpp v42, v42 quad_perm:[1,0,3,2] row_mask:0xf bank_mask:0xf
	s_nop 1
	v_mov_b32_dpp v43, v43 quad_perm:[1,0,3,2] row_mask:0xf bank_mask:0xf
	v_cndmask_b32_e64 v35, v48, v47, s[4:5]
	v_lshl_add_u64 v[38:39], v[86:87], 0, v[38:39]
	v_pk_mul_f32 v[30:31], v[30:31], v[90:91] op_sel_hi:[1,0]
	v_pk_mul_f32 v[26:27], v[26:27], v[90:91] op_sel_hi:[1,0]
	v_pk_mul_f32 v[28:29], v[28:29], v[90:91] op_sel_hi:[1,0]
	v_pk_mul_f32 v[24:25], v[24:25], v[90:91] op_sel_hi:[1,0]
	v_pk_mul_f32 v[18:19], v[18:19], v[90:91] op_sel_hi:[1,0]
	global_store_dwordx4 v[38:39], v[34:37], off
	v_pk_mul_f32 v[32:33], v[32:33], v[90:91] op_sel_hi:[1,0]
	v_pk_mul_f32 v[30:31], v[2:3], v[30:31]
	s_waitcnt lgkmcnt(1)
	v_cndmask_b32_e64 v36, v41, v42, s[4:5]
	v_cndmask_b32_e64 v34, v42, v44, s[4:5]
	s_waitcnt lgkmcnt(0)
	v_cndmask_b32_e64 v37, v45, v43, s[4:5]
	v_cndmask_b32_e64 v35, v43, v40, s[4:5]
	v_pk_mul_f32 v[28:29], v[8:9], v[28:29]
	v_pk_mul_f32 v[26:27], v[6:7], v[26:27]
	v_pk_mul_f32 v[22:23], v[22:23], v[90:91] op_sel_hi:[1,0]
	v_pk_mul_f32 v[24:25], v[12:13], v[24:25]
	v_pk_mul_f32 v[20:21], v[20:21], v[90:91] op_sel_hi:[1,0]
	v_pk_mul_f32 v[18:19], v[14:15], v[18:19]
	global_store_dwordx4 v[38:39], v[34:37], off offset:1024
	v_pk_mul_f32 v[32:33], v[4:5], v[32:33]
	v_cvt_pk_bf16_f32 v30, v30, v31
	v_pk_mul_f32 v[22:23], v[10:11], v[22:23]
	v_cvt_pk_bf16_f32 v31, v32, v33
	v_cvt_pk_bf16_f32 v26, v26, v27
	v_cvt_pk_bf16_f32 v27, v28, v29
	v_pk_mul_f32 v[20:21], v[16:17], v[20:21]
	v_cvt_pk_bf16_f32 v28, v22, v23
	v_cvt_pk_bf16_f32 v24, v24, v25
	v_cvt_pk_bf16_f32 v25, v18, v19
	v_cndmask_b32_e64 v19, v30, v26, s[4:5]
	v_cvt_pk_bf16_f32 v29, v20, v21
	s_nop 1
	v_mov_b32_dpp v21, v19 quad_perm:[1,0,3,2] row_mask:0xf bank_mask:0xf
	v_cndmask_b32_e64 v19, v31, v27, s[4:5]
	s_nop 1
	v_mov_b32_dpp v32, v19 quad_perm:[1,0,3,2] row_mask:0xf bank_mask:0xf
	v_add_u32_e32 v18, 3, v88
	v_ashrrev_i32_e32 v19, 31, v18
	v_lshlrev_b64 v[22:23], 11, v[18:19]
	s_waitcnt lgkmcnt(1)
	v_cndmask_b32_e64 v20, v26, v21, s[4:5]
	v_cndmask_b32_e64 v18, v21, v30, s[4:5]
	s_waitcnt lgkmcnt(0)
	v_cndmask_b32_e64 v21, v27, v32, s[4:5]
	v_cndmask_b32_e64 v26, v28, v25, s[4:5]
	v_cndmask_b32_e64 v27, v24, v29, s[4:5]
	s_nop 1
	v_mov_b32_dpp v26, v26 quad_perm:[1,0,3,2] row_mask:0xf bank_mask:0xf
	s_nop 1
	v_mov_b32_dpp v27, v27 quad_perm:[1,0,3,2] row_mask:0xf bank_mask:0xf
	v_cndmask_b32_e64 v19, v32, v31, s[4:5]
	v_lshl_add_u64 v[22:23], v[86:87], 0, v[22:23]
	global_store_dwordx4 v[22:23], v[18:21], off
	s_waitcnt lgkmcnt(1)
	s_nop 0
	v_cndmask_b32_e64 v20, v25, v26, s[4:5]
	v_cndmask_b32_e64 v18, v26, v28, s[4:5]
	s_waitcnt lgkmcnt(0)
	v_cndmask_b32_e64 v21, v29, v27, s[4:5]
	v_cndmask_b32_e64 v19, v27, v24, s[4:5]
	global_store_dwordx4 v[22:23], v[18:21], off offset:1024

	.amdhsa_kernel _Z9hymba_fwd6Params
		.amdhsa_group_segment_fixed_size 0
		.amdhsa_private_segment_fixed_size 0
		.amdhsa_kernarg_size 424
		.amdhsa_user_sgpr_count 2
		.amdhsa_user_sgpr_dispatch_ptr 0
		.amdhsa_user_sgpr_queue_ptr 0
		.amdhsa_user_sgpr_kernarg_segment_ptr 1
		.amdhsa_user_sgpr_dispatch_id 0
		.amdhsa_user_sgpr_kernarg_preload_length 0
		.amdhsa_user_sgpr_kernarg_preload_offset 0
		.amdhsa_user_sgpr_private_segment_size 0
		.amdhsa_uses_dynamic_stack 0
		.amdhsa_enable_private_segment 0
		.amdhsa_system_sgpr_workgroup_id_x 1
		.amdhsa_system_sgpr_workgroup_id_y 0
		.amdhsa_system_sgpr_workgroup_id_z 0
		.amdhsa_system_sgpr_workgroup_info 0
		.amdhsa_system_vgpr_workitem_id 0
		.amdhsa_next_free_vgpr 256
		.amdhsa_next_free_sgpr 102
		.amdhsa_accum_offset 256
		.amdhsa_reserve_vcc 1
		.amdhsa_float_round_mode_32 0
		.amdhsa_float_round_mode_16_64 0
		.amdhsa_float_denorm_mode_32 3
		.amdhsa_float_denorm_mode_16_64 3
		.amdhsa_dx10_clamp 1
		.amdhsa_ieee_mode 1
		.amdhsa_fp16_overflow 0
		.amdhsa_tg_split 0
		.amdhsa_exception_fp_ieee_invalid_op 0
		.amdhsa_exception_fp_denorm_src 0
		.amdhsa_exception_fp_ieee_div_zero 0
		.amdhsa_exception_fp_ieee_overflow 0
		.amdhsa_exception_fp_ieee_underflow 0
		.amdhsa_exception_fp_ieee_inexact 0
		.amdhsa_exception_int_div_zero 0
	.end_amdhsa_kernel

amdhsa.kernels:
  - .agpr_count:     0
    .args:
      - .offset:         0
        .size:           168
        .value_kind:     by_value
      - .offset:         168
        .size:           4
        .value_kind:     hidden_block_count_x
      - .offset:         172
        .size:           4
        .value_kind:     hidden_block_count_y
      - .offset:         176
        .size:           4
        .value_kind:     hidden_block_count_z
      - .offset:         180
        .size:           2
        .value_kind:     hidden_group_size_x
      - .offset:         182
        .size:           2
        .value_kind:     hidden_group_size_y
      - .offset:         184
        .size:           2
        .value_kind:     hidden_group_size_z
      - .offset:         186
        .size:           2
        .value_kind:     hidden_remainder_x
      - .offset:         188
        .size:           2
        .value_kind:     hidden_remainder_y
      - .offset:         190
        .size:           2
        .value_kind:     hidden_remainder_z
      - .offset:         208
        .size:           8
        .value_kind:     hidden_global_offset_x
      - .offset:         216
        .size:           8
        .value_kind:     hidden_global_offset_y
      - .offset:         224
        .size:           8
        .value_kind:     hidden_global_offset_z
      - .offset:         232
        .size:           2
        .value_kind:     hidden_grid_dims
      - .offset:         288
        .size:           4
        .value_kind:     hidden_dynamic_lds_size
    .group_segment_fixed_size: 0
    .kernarg_segment_align: 8
    .kernarg_segment_size: 424
    .language:       OpenCL C
    .language_version:
      - 2
      - 0
    .max_flat_workgroup_size: 512
    .name:           _Z9hymba_fwd6Params
    .private_segment_fixed_size: 0
    .sgpr_count:     108
    .sgpr_spill_count: 27
    .symbol:         _Z9hymba_fwd6Params.kd
    .uniform_work_group_size: 1
    .uses_dynamic_stack: false
    .vgpr_count:     256
    .vgpr_spill_count: 0
    .wavefront_size: 64
